# tail_convert stores take the nt hint (converted weights are consumed a layer later; keep val / XBCP cache-resident instead)
# speedup vs baseline: 1.0034x; 1.0034x over previous
; #define LAS __attribute__((address_space(3)))
; __device__ __forceinline__ unsigned cvt_pk_bf16(float lo, float hi) { const f32x2 v = {lo, hi}; return __builtin_bit_cast(unsigned, __builtin_convertvector(v, bf16x2_t)); }
; #define LDS_WAIT() asm volatile("s_waitcnt lgkmcnt(0)" ::: "memory")
; __device__ __forceinline__ void tail_convert(Frame& F, int total_units, const float* W0, bf16_t* WT0, int K0, int N0, int perm0, const float* W1, bf16_t* WT1, int K1, int N1) {
;     ...
;     f32x4 v[8];
;     int it = slot;
;     if (it < n0 + n1) { const float* W; bf16_t* WT; int K, N, k0, nn0, dr; TC_ITEM(it, W, WT, K, N, k0, nn0, dr); (void)WT; (void)K; (void)dr;
; #pragma unroll
;         for (int i = 0; i < 8; ++i) v[i] = __builtin_nontemporal_load((const f32x4*)(W + (size_t)(k0 + 8 * i + kk) * N + nn0 + nq)); }
;     for (; it < n0 + n1; it += nslots) {
;         const float* W; bf16_t* WT; int K, N, k0, nn0, dr; TC_ITEM(it, W, WT, K, N, k0, nn0, dr); (void)W;
; #pragma unroll
;         for (int i = 0; i < 8; ++i) { LAS float* d = scr + (8 * i + kk) * 33 + nq; d[0] = v[i].x; d[1] = v[i].y; d[2] = v[i].z; d[3] = v[i].w; }
;         const int itn = it + nslots;
;         if (itn < n0 + n1) { const float* Wn; bf16_t* WTn; int Kn, Nn, k0n, n0n, drn; TC_ITEM(itn, Wn, WTn, Kn, Nn, k0n, n0n, drn); (void)WTn; (void)Kn; (void)drn;
; #pragma unroll
;             for (int i = 0; i < 8; ++i) v[i] = __builtin_nontemporal_load((const f32x4*)(Wn + (size_t)(k0n + 8 * i + kk) * Nn + n0n + nq)); }
;         LDS_WAIT(); asm volatile("" ::: "memory");
; #pragma unroll
;         for (int j = 0; j < 4; ++j) { const int n = (lane >> 3) + 8 * j; const LAS float* sp = scr + (8 * c) * 33 + n;
;             u32x4 o; o.x = cvt_pk_bf16(sp[0 * 33], sp[1 * 33]); o.y = cvt_pk_bf16(sp[2 * 33], sp[3 * 33]); o.z = cvt_pk_bf16(sp[4 * 33], sp[5 * 33]); o.w = cvt_pk_bf16(sp[6 * 33], sp[7 * 33]);
;             *(u32x4*)(WT + (size_t)(dr + n) * K + k0 + 8 * c) = o; }
;         LDS_WAIT(); asm volatile("" ::: "memory");
.LBB0_320:
	s_add_i32 s4, s11, s1
	s_mul_hi_i32 s4, s4, 0x2e8ba2e9
	s_lshr_b32 s5, s4, 31
	s_ashr_i32 s4, s4, 6
	s_add_i32 s6, s4, s5
	s_lshl_b32 s4, s6, 6
	s_waitcnt lgkmcnt(0)
	s_ashr_i32 s5, s4, 31
	v_lshl_add_u64 v[44:45], s[4:5], 1, v[34:35]
	ds_read2_b32 v[46:47], v37 offset0:33 offset1:41
	ds_read2_b32 v[48:49], v37 offset1:8
	ds_read2_b32 v[50:51], v37 offset0:66 offset1:74
	ds_read2_b32 v[52:53], v37 offset0:99 offset1:107
	ds_read2_b32 v[54:55], v37 offset0:132 offset1:140
	ds_read2_b32 v[56:57], v37 offset0:165 offset1:173
	ds_read2_b32 v[58:59], v37 offset0:198 offset1:206
	ds_read2_b32 v[60:61], v37 offset0:231 offset1:239
	s_mul_i32 s4, s6, 0xffffd400
	s_add_i32 s4, s4, s0
	v_add_u32_e32 v62, s4, v38
	v_ashrrev_i32_e32 v63, 31, v62
	v_lshlrev_b64 v[64:65], 12, v[62:63]
	s_waitcnt lgkmcnt(6)
	v_cvt_pk_bf16_f32 v40, v48, v46
	s_waitcnt lgkmcnt(4)
	v_cvt_pk_bf16_f32 v41, v50, v52
	s_waitcnt lgkmcnt(2)
	v_cvt_pk_bf16_f32 v42, v54, v56
	s_waitcnt lgkmcnt(0)
	v_cvt_pk_bf16_f32 v43, v58, v60
	v_lshl_add_u64 v[64:65], v[44:45], 0, v[64:65]
	v_add_u32_e32 v46, 8, v62
	global_store_dwordx4 v[64:65], v[40:43], off nt
	v_add_u32_e32 v64, 16, v62
	v_ashrrev_i32_e32 v65, 31, v64
	v_cvt_pk_bf16_f32 v40, v49, v47
	v_ashrrev_i32_e32 v47, 31, v46
	v_lshlrev_b64 v[46:47], 12, v[46:47]
	v_cvt_pk_bf16_f32 v41, v51, v53
	v_cvt_pk_bf16_f32 v42, v55, v57
	v_cvt_pk_bf16_f32 v43, v59, v61
	v_lshl_add_u64 v[46:47], v[44:45], 0, v[46:47]
	global_store_dwordx4 v[46:47], v[40:43], off nt
	ds_read2_b32 v[46:47], v37 offset0:49 offset1:57
	ds_read2_b32 v[48:49], v37 offset0:16 offset1:24
	ds_read2_b32 v[50:51], v37 offset0:82 offset1:90
	ds_read2_b32 v[52:53], v37 offset0:115 offset1:123
	ds_read2_b32 v[54:55], v37 offset0:148 offset1:156
	ds_read2_b32 v[56:57], v37 offset0:181 offset1:189
	ds_read2_b32 v[58:59], v37 offset0:214 offset1:222
	ds_read2_b32 v[60:61], v37 offset0:247 offset1:255
	v_lshlrev_b64 v[64:65], 12, v[64:65]
	s_waitcnt lgkmcnt(6)
	v_cvt_pk_bf16_f32 v40, v48, v46
	s_waitcnt lgkmcnt(4)
	v_cvt_pk_bf16_f32 v41, v50, v52
	s_waitcnt lgkmcnt(2)
	v_cvt_pk_bf16_f32 v42, v54, v56
	s_waitcnt lgkmcnt(0)
	v_cvt_pk_bf16_f32 v43, v58, v60
	v_lshl_add_u64 v[64:65], v[44:45], 0, v[64:65]
	v_add_u32_e32 v46, 24, v62
	global_store_dwordx4 v[64:65], v[40:43], off nt
	s_add_i32 s1, s1, s7
	s_add_i32 s0, s0, s10
	v_cvt_pk_bf16_f32 v40, v49, v47
	v_ashrrev_i32_e32 v47, 31, v46
	v_lshlrev_b64 v[46:47], 12, v[46:47]
	v_cvt_pk_bf16_f32 v41, v51, v53
	v_cvt_pk_bf16_f32 v42, v55, v57
	v_cvt_pk_bf16_f32 v43, v59, v61
	v_lshl_add_u64 v[44:45], v[44:45], 0, v[46:47]
	global_store_dwordx4 v[44:45], v[40:43], off nt
	s_waitcnt lgkmcnt(0)
	s_add_i32 s4, s11, s1
	s_cmpk_lt_i32 s4, 0x2c00
	s_cbranch_scc0 .LBB0_323

; #define LAS __attribute__((address_space(3)))
; __device__ __forceinline__ unsigned cvt_pk_bf16(float lo, float hi) { const f32x2 v = {lo, hi}; return __builtin_bit_cast(unsigned, __builtin_convertvector(v, bf16x2_t)); }
; #define LDS_WAIT() asm volatile("s_waitcnt lgkmcnt(0)" ::: "memory")
; __device__ __forceinline__ void tail_convert(Frame& F, int total_units, const float* W0, bf16_t* WT0, int K0, int N0, int perm0, const float* W1, bf16_t* WT1, int K1, int N1) {
;     ...
;     f32x4 v[8];
;     int it = slot;
;     if (it < n0 + n1) { const float* W; bf16_t* WT; int K, N, k0, nn0, dr; TC_ITEM(it, W, WT, K, N, k0, nn0, dr); (void)WT; (void)K; (void)dr;
; #pragma unroll
;         for (int i = 0; i < 8; ++i) v[i] = __builtin_nontemporal_load((const f32x4*)(W + (size_t)(k0 + 8 * i + kk) * N + nn0 + nq)); }
;     for (; it < n0 + n1; it += nslots) {
;         const float* W; bf16_t* WT; int K, N, k0, nn0, dr; TC_ITEM(it, W, WT, K, N, k0, nn0, dr); (void)W;
; #pragma unroll
;         for (int i = 0; i < 8; ++i) { LAS float* d = scr + (8 * i + kk) * 33 + nq; d[0] = v[i].x; d[1] = v[i].y; d[2] = v[i].z; d[3] = v[i].w; }
;         const int itn = it + nslots;
;         if (itn < n0 + n1) { const float* Wn; bf16_t* WTn; int Kn, Nn, k0n, n0n, drn; TC_ITEM(itn, Wn, WTn, Kn, Nn, k0n, n0n, drn); (void)WTn; (void)Kn; (void)drn;
; #pragma unroll
;             for (int i = 0; i < 8; ++i) v[i] = __builtin_nontemporal_load((const f32x4*)(Wn + (size_t)(k0n + 8 * i + kk) * Nn + n0n + nq)); }
;         LDS_WAIT(); asm volatile("" ::: "memory");
; #pragma unroll
;         for (int j = 0; j < 4; ++j) { const int n = (lane >> 3) + 8 * j; const LAS float* sp = scr + (8 * c) * 33 + n;
;             u32x4 o; o.x = cvt_pk_bf16(sp[0 * 33], sp[1 * 33]); o.y = cvt_pk_bf16(sp[2 * 33], sp[3 * 33]); o.z = cvt_pk_bf16(sp[4 * 33], sp[5 * 33]); o.w = cvt_pk_bf16(sp[6 * 33], sp[7 * 33]);
;             *(u32x4*)(WT + (size_t)(dr + n) * K + k0 + 8 * c) = o; }
;         LDS_WAIT(); asm volatile("" ::: "memory");
.LBB0_891:
	s_add_i32 s4, s14, s1
	s_waitcnt lgkmcnt(0)
	s_ashr_i32 s5, s4, 31
	s_lshr_b32 s5, s5, 26
	ds_read2_b32 v[46:47], v37 offset0:33 offset1:41
	ds_read2_b32 v[48:49], v37 offset1:8
	s_add_i32 s6, s4, s5
	s_and_b32 s4, s6, 0xffffffc0
	ds_read2_b32 v[50:51], v37 offset0:66 offset1:74
	ds_read2_b32 v[52:53], v37 offset0:99 offset1:107
	ds_read2_b32 v[54:55], v37 offset0:132 offset1:140
	ds_read2_b32 v[56:57], v37 offset0:165 offset1:173
	ds_read2_b32 v[58:59], v37 offset0:198 offset1:206
	ds_read2_b32 v[60:61], v37 offset0:231 offset1:239
	s_ashr_i32 s5, s4, 31
	v_lshl_add_u64 v[44:45], s[4:5], 1, v[34:35]
	s_lshl_b32 s4, s6, 5
	s_waitcnt lgkmcnt(6)
	v_cvt_pk_bf16_f32 v40, v48, v46
	v_add_u32_e32 v46, s0, v38
	s_and_b32 s4, s4, 0xfffff800
	v_subrev_u32_e32 v64, s4, v46
	s_waitcnt lgkmcnt(4)
	v_cvt_pk_bf16_f32 v41, v50, v52
	s_waitcnt lgkmcnt(2)
	v_cvt_pk_bf16_f32 v42, v54, v56
	s_waitcnt lgkmcnt(0)
	v_cvt_pk_bf16_f32 v43, v58, v60
	v_mad_i64_i32 v[62:63], s[4:5], v64, s89, v[44:45]
	v_add_u32_e32 v46, 8, v64
	global_store_dwordx4 v[62:63], v[40:43], off nt
	s_add_i32 s1, s1, s7
	s_add_i32 s0, s0, s10
	v_cvt_pk_bf16_f32 v40, v49, v47
	v_cvt_pk_bf16_f32 v41, v51, v53
	v_cvt_pk_bf16_f32 v42, v55, v57
	v_cvt_pk_bf16_f32 v43, v59, v61
	v_mad_i64_i32 v[46:47], s[4:5], v46, s89, v[44:45]
	global_store_dwordx4 v[46:47], v[40:43], off nt
	ds_read2_b32 v[46:47], v37 offset0:49 offset1:57
	ds_read2_b32 v[48:49], v37 offset0:16 offset1:24
	ds_read2_b32 v[50:51], v37 offset0:82 offset1:90
	ds_read2_b32 v[52:53], v37 offset0:115 offset1:123
	ds_read2_b32 v[54:55], v37 offset0:148 offset1:156
	ds_read2_b32 v[56:57], v37 offset0:181 offset1:189
	ds_read2_b32 v[58:59], v37 offset0:214 offset1:222
	ds_read2_b32 v[60:61], v37 offset0:247 offset1:255
	s_waitcnt lgkmcnt(6)
	v_cvt_pk_bf16_f32 v40, v48, v46
	v_add_u32_e32 v46, 16, v64
	s_waitcnt lgkmcnt(4)
	v_cvt_pk_bf16_f32 v41, v50, v52
	s_waitcnt lgkmcnt(2)
	v_cvt_pk_bf16_f32 v42, v54, v56
	s_waitcnt lgkmcnt(0)
	v_cvt_pk_bf16_f32 v43, v58, v60
	v_mad_i64_i32 v[62:63], s[4:5], v46, s89, v[44:45]
	v_add_u32_e32 v46, 24, v64
	global_store_dwordx4 v[62:63], v[40:43], off nt
	v_mad_i64_i32 v[44:45], s[4:5], v46, s89, v[44:45]
	s_nop 0
	v_cvt_pk_bf16_f32 v40, v49, v47
	v_cvt_pk_bf16_f32 v41, v51, v53
	v_cvt_pk_bf16_f32 v42, v55, v57
	v_cvt_pk_bf16_f32 v43, v59, v61
	global_store_dwordx4 v[44:45], v[40:43], off nt
	s_waitcnt lgkmcnt(0)
	s_add_i32 s4, s14, s1
	s_cmpk_lt_i32 s4, 0x1600
	s_cbranch_scc0 .LBB0_894

; #define LAS __attribute__((address_space(3)))
; __device__ __forceinline__ unsigned cvt_pk_bf16(float lo, float hi) { const f32x2 v = {lo, hi}; return __builtin_bit_cast(unsigned, __builtin_convertvector(v, bf16x2_t)); }
; #define LDS_WAIT() asm volatile("s_waitcnt lgkmcnt(0)" ::: "memory")
; __device__ __forceinline__ void tail_convert(Frame& F, int total_units, const float* W0, bf16_t* WT0, int K0, int N0, int perm0, const float* W1, bf16_t* WT1, int K1, int N1) {
;     ...
;     f32x4 v[8];
;     int it = slot;
;     if (it < n0 + n1) { const float* W; bf16_t* WT; int K, N, k0, nn0, dr; TC_ITEM(it, W, WT, K, N, k0, nn0, dr); (void)WT; (void)K; (void)dr;
; #pragma unroll
;         for (int i = 0; i < 8; ++i) v[i] = __builtin_nontemporal_load((const f32x4*)(W + (size_t)(k0 + 8 * i + kk) * N + nn0 + nq)); }
;     for (; it < n0 + n1; it += nslots) {
;         const float* W; bf16_t* WT; int K, N, k0, nn0, dr; TC_ITEM(it, W, WT, K, N, k0, nn0, dr); (void)W;
; #pragma unroll
;         for (int i = 0; i < 8; ++i) { LAS float* d = scr + (8 * i + kk) * 33 + nq; d[0] = v[i].x; d[1] = v[i].y; d[2] = v[i].z; d[3] = v[i].w; }
;         const int itn = it + nslots;
;         if (itn < n0 + n1) { const float* Wn; bf16_t* WTn; int Kn, Nn, k0n, n0n, drn; TC_ITEM(itn, Wn, WTn, Kn, Nn, k0n, n0n, drn); (void)WTn; (void)Kn; (void)drn;
; #pragma unroll
;             for (int i = 0; i < 8; ++i) v[i] = __builtin_nontemporal_load((const f32x4*)(Wn + (size_t)(k0n + 8 * i + kk) * Nn + n0n + nq)); }
;         LDS_WAIT(); asm volatile("" ::: "memory");
; #pragma unroll
;         for (int j = 0; j < 4; ++j) { const int n = (lane >> 3) + 8 * j; const LAS float* sp = scr + (8 * c) * 33 + n;
;             u32x4 o; o.x = cvt_pk_bf16(sp[0 * 33], sp[1 * 33]); o.y = cvt_pk_bf16(sp[2 * 33], sp[3 * 33]); o.z = cvt_pk_bf16(sp[4 * 33], sp[5 * 33]); o.w = cvt_pk_bf16(sp[6 * 33], sp[7 * 33]);
;             *(u32x4*)(WT + (size_t)(dr + n) * K + k0 + 8 * c) = o; }
;         LDS_WAIT(); asm volatile("" ::: "memory");
.LBB0_1130:
	s_add_i32 s17, s36, s30
	s_cmpk_gt_i32 s17, 0x7ff
	s_cselect_b32 s34, 0x160, 64
	v_cvt_f32_u32_e32 v33, s34
	s_cselect_b32 s27, 0xfffff800, 0
	s_cselect_b32 s38, s26, s7
	s_cselect_b32 s39, s15, s6
	v_rcp_iflag_f32_e32 v33, v33
	s_add_i32 s35, s17, s27
	s_ashr_i32 s35, s35, 31
	s_sub_i32 s41, 0, s34
	v_mul_f32_e32 v33, 0x4f7ffffe, v33
	v_cvt_u32_f32_e32 v33, v33
	s_add_i32 s40, s27, s35
	s_add_i32 s40, s17, s40
	s_xor_b32 s40, s40, s35
	v_readfirstlane_b32 s42, v33
	s_mul_i32 s41, s41, s42
	s_mul_hi_u32 s41, s42, s41
	s_add_i32 s42, s42, s41
	s_mul_hi_u32 s41, s40, s42
	s_mul_i32 s42, s41, s34
	s_sub_i32 s40, s40, s42
	s_add_i32 s42, s41, 1
	s_sub_i32 s43, s40, s34
	s_cmp_ge_u32 s40, s34
	s_cselect_b32 s41, s42, s41
	s_cselect_b32 s40, s43, s40
	s_add_i32 s42, s41, 1
	s_cmp_ge_u32 s40, s34
	s_cselect_b32 s40, s42, s41
	s_xor_b32 s40, s40, s35
	s_sub_i32 s35, s40, s35
	s_mul_i32 s34, s35, s34
	s_waitcnt lgkmcnt(0)
	s_sub_i32 s27, s27, s34
	s_lshl_b32 s34, s35, 6
	s_ashr_i32 s35, s34, 31
	ds_read2_b32 v[44:45], v35 offset0:33 offset1:41
	ds_read2_b32 v[46:47], v35 offset1:8
	ds_read2_b32 v[48:49], v35 offset0:66 offset1:74
	ds_read2_b32 v[50:51], v35 offset0:99 offset1:107
	ds_read2_b32 v[52:53], v35 offset0:132 offset1:140
	ds_read2_b32 v[54:55], v35 offset0:165 offset1:173
	ds_read2_b32 v[56:57], v35 offset0:198 offset1:206
	ds_read2_b32 v[58:59], v35 offset0:231 offset1:239
	s_add_i32 s17, s17, s27
	s_lshl_b64 s[34:35], s[34:35], 1
	s_add_u32 s34, s39, s34
	v_lshl_add_u32 v60, s17, 5, v34
	s_addc_u32 s35, s38, s35
	v_ashrrev_i32_e32 v61, 31, v60
	v_lshl_add_u64 v[42:43], s[34:35], 0, v[176:177]
	v_lshlrev_b64 v[62:63], 12, v[60:61]
	s_waitcnt lgkmcnt(6)
	v_cvt_pk_bf16_f32 v38, v46, v44
	s_waitcnt lgkmcnt(4)
	v_cvt_pk_bf16_f32 v39, v48, v50
	s_waitcnt lgkmcnt(2)
	v_cvt_pk_bf16_f32 v40, v52, v54
	s_waitcnt lgkmcnt(0)
	v_cvt_pk_bf16_f32 v41, v56, v58
	v_lshl_add_u64 v[62:63], v[42:43], 0, v[62:63]
	v_add_u32_e32 v44, 8, v60
	global_store_dwordx4 v[62:63], v[38:41], off nt
	v_add_u32_e32 v62, 16, v60
	v_ashrrev_i32_e32 v63, 31, v62
	v_cvt_pk_bf16_f32 v38, v47, v45
	v_ashrrev_i32_e32 v45, 31, v44
	v_lshlrev_b64 v[44:45], 12, v[44:45]
	v_cvt_pk_bf16_f32 v39, v49, v51
	v_cvt_pk_bf16_f32 v40, v53, v55
	v_cvt_pk_bf16_f32 v41, v57, v59
	v_lshl_add_u64 v[44:45], v[42:43], 0, v[44:45]
	global_store_dwordx4 v[44:45], v[38:41], off nt
	ds_read2_b32 v[44:45], v35 offset0:49 offset1:57
	ds_read2_b32 v[46:47], v35 offset0:16 offset1:24
	ds_read2_b32 v[48:49], v35 offset0:82 offset1:90
	ds_read2_b32 v[50:51], v35 offset0:115 offset1:123
	ds_read2_b32 v[52:53], v35 offset0:148 offset1:156
	ds_read2_b32 v[54:55], v35 offset0:181 offset1:189
	ds_read2_b32 v[56:57], v35 offset0:214 offset1:222
	ds_read2_b32 v[58:59], v35 offset0:247 offset1:255
	v_lshlrev_b64 v[62:63], 12, v[62:63]
	s_waitcnt lgkmcnt(6)
	v_cvt_pk_bf16_f32 v38, v46, v44
	s_waitcnt lgkmcnt(4)
	v_cvt_pk_bf16_f32 v39, v48, v50
	s_waitcnt lgkmcnt(2)
	v_cvt_pk_bf16_f32 v40, v52, v54
	s_waitcnt lgkmcnt(0)
	v_cvt_pk_bf16_f32 v41, v56, v58
	v_lshl_add_u64 v[62:63], v[42:43], 0, v[62:63]
	v_add_u32_e32 v44, 24, v60
	global_store_dwordx4 v[62:63], v[38:41], off nt
	s_add_i32 s30, s30, s0
	s_add_i32 s17, s36, s30
	v_cvt_pk_bf16_f32 v38, v47, v45
	v_ashrrev_i32_e32 v45, 31, v44
	v_lshlrev_b64 v[44:45], 12, v[44:45]
	v_cvt_pk_bf16_f32 v39, v49, v51
	v_cvt_pk_bf16_f32 v40, v53, v55
	v_cvt_pk_bf16_f32 v41, v57, v59
	v_lshl_add_u64 v[42:43], v[42:43], 0, v[44:45]
	global_store_dwordx4 v[42:43], v[38:41], off nt
	s_waitcnt lgkmcnt(0)
	s_add_i32 s31, s31, s0
	s_cmpk_lt_i32 s17, 0x3400
	s_cbranch_scc0 .LBB0_1133

; #define LAS __attribute__((address_space(3)))
; __device__ __forceinline__ unsigned cvt_pk_bf16(float lo, float hi) { const f32x2 v = {lo, hi}; return __builtin_bit_cast(unsigned, __builtin_convertvector(v, bf16x2_t)); }
; #define LDS_WAIT() asm volatile("s_waitcnt lgkmcnt(0)" ::: "memory")
; __device__ __forceinline__ void tail_convert(Frame& F, int total_units, const float* W0, bf16_t* WT0, int K0, int N0, int perm0, const float* W1, bf16_t* WT1, int K1, int N1) {
;     ...
;     f32x4 v[8];
;     int it = slot;
;     if (it < n0 + n1) { const float* W; bf16_t* WT; int K, N, k0, nn0, dr; TC_ITEM(it, W, WT, K, N, k0, nn0, dr); (void)WT; (void)K; (void)dr;
; #pragma unroll
;         for (int i = 0; i < 8; ++i) v[i] = __builtin_nontemporal_load((const f32x4*)(W + (size_t)(k0 + 8 * i + kk) * N + nn0 + nq)); }
;     for (; it < n0 + n1; it += nslots) {
;         const float* W; bf16_t* WT; int K, N, k0, nn0, dr; TC_ITEM(it, W, WT, K, N, k0, nn0, dr); (void)W;
; #pragma unroll
;         for (int i = 0; i < 8; ++i) { LAS float* d = scr + (8 * i + kk) * 33 + nq; d[0] = v[i].x; d[1] = v[i].y; d[2] = v[i].z; d[3] = v[i].w; }
;         const int itn = it + nslots;
;         if (itn < n0 + n1) { const float* Wn; bf16_t* WTn; int Kn, Nn, k0n, n0n, drn; TC_ITEM(itn, Wn, WTn, Kn, Nn, k0n, n0n, drn); (void)WTn; (void)Kn; (void)drn;
; #pragma unroll
;             for (int i = 0; i < 8; ++i) v[i] = __builtin_nontemporal_load((const f32x4*)(Wn + (size_t)(k0n + 8 * i + kk) * Nn + n0n + nq)); }
;         LDS_WAIT(); asm volatile("" ::: "memory");
; #pragma unroll
;         for (int j = 0; j < 4; ++j) { const int n = (lane >> 3) + 8 * j; const LAS float* sp = scr + (8 * c) * 33 + n;
;             u32x4 o; o.x = cvt_pk_bf16(sp[0 * 33], sp[1 * 33]); o.y = cvt_pk_bf16(sp[2 * 33], sp[3 * 33]); o.z = cvt_pk_bf16(sp[4 * 33], sp[5 * 33]); o.w = cvt_pk_bf16(sp[6 * 33], sp[7 * 33]);
;             *(u32x4*)(WT + (size_t)(dr + n) * K + k0 + 8 * c) = o; }
;         LDS_WAIT(); asm volatile("" ::: "memory");
.LBB0_1138:
	s_and_b64 s[4:5], s[0:1], exec
	s_cselect_b32 s17, s11, s26
	s_cselect_b32 s27, s10, s15
	s_lshl_b32 s4, s37, 6
	s_waitcnt lgkmcnt(0)
	s_ashr_i32 s5, s4, 31
	s_lshl_b64 s[4:5], s[4:5], 1
	s_add_u32 s4, s27, s4
	ds_read2_b32 v[44:45], v35 offset0:33 offset1:41
	ds_read2_b32 v[46:47], v35 offset1:8
	ds_read2_b32 v[48:49], v35 offset0:66 offset1:74
	ds_read2_b32 v[50:51], v35 offset0:99 offset1:107
	ds_read2_b32 v[52:53], v35 offset0:132 offset1:140
	ds_read2_b32 v[54:55], v35 offset0:165 offset1:173
	ds_read2_b32 v[56:57], v35 offset0:198 offset1:206
	ds_read2_b32 v[58:59], v35 offset0:231 offset1:239
	s_addc_u32 s5, s17, s5
	v_add_u32_e32 v60, s36, v34
	s_and_b64 s[0:1], s[0:1], exec
	v_ashrrev_i32_e32 v61, 31, v60
	s_cselect_b32 s0, 12, 11
	v_lshl_add_u64 v[42:43], s[4:5], 0, v[176:177]
	v_lshlrev_b64 v[62:63], s0, v[60:61]
	s_waitcnt lgkmcnt(6)
	v_cvt_pk_bf16_f32 v38, v46, v44
	s_waitcnt lgkmcnt(4)
	v_cvt_pk_bf16_f32 v39, v48, v50
	s_waitcnt lgkmcnt(2)
	v_cvt_pk_bf16_f32 v40, v52, v54
	s_waitcnt lgkmcnt(0)
	v_cvt_pk_bf16_f32 v41, v56, v58
	v_lshl_add_u64 v[62:63], v[62:63], 1, v[42:43]
	v_add_u32_e32 v44, 8, v60
	global_store_dwordx4 v[62:63], v[38:41], off nt
	v_add_u32_e32 v62, 16, v60
	v_ashrrev_i32_e32 v63, 31, v62
	v_cvt_pk_bf16_f32 v38, v47, v45
	v_ashrrev_i32_e32 v45, 31, v44
	v_lshlrev_b64 v[44:45], s0, v[44:45]
	v_cvt_pk_bf16_f32 v39, v49, v51
	v_cvt_pk_bf16_f32 v40, v53, v55
	v_cvt_pk_bf16_f32 v41, v57, v59
	v_lshl_add_u64 v[44:45], v[44:45], 1, v[42:43]
	global_store_dwordx4 v[44:45], v[38:41], off nt
	ds_read2_b32 v[44:45], v35 offset0:16 offset1:24
	ds_read2_b32 v[46:47], v35 offset0:49 offset1:57
	ds_read2_b32 v[48:49], v35 offset0:82 offset1:90
	ds_read2_b32 v[50:51], v35 offset0:115 offset1:123
	ds_read2_b32 v[52:53], v35 offset0:148 offset1:156
	ds_read2_b32 v[54:55], v35 offset0:181 offset1:189
	ds_read2_b32 v[56:57], v35 offset0:214 offset1:222
	ds_read2_b32 v[58:59], v35 offset0:247 offset1:255
	v_lshlrev_b64 v[62:63], s0, v[62:63]
	s_waitcnt lgkmcnt(6)
	v_cvt_pk_bf16_f32 v38, v44, v46
	s_waitcnt lgkmcnt(4)
	v_cvt_pk_bf16_f32 v39, v48, v50
	s_waitcnt lgkmcnt(2)
	v_cvt_pk_bf16_f32 v40, v52, v54
	s_waitcnt lgkmcnt(0)
	v_cvt_pk_bf16_f32 v41, v56, v58
	v_lshl_add_u64 v[62:63], v[62:63], 1, v[42:43]
	v_add_u32_e32 v44, 24, v60
	global_store_dwordx4 v[62:63], v[38:41], off nt
	s_add_i32 s34, s34, s6
	s_add_i32 s35, s35, s6
	v_cvt_pk_bf16_f32 v38, v45, v47
	v_ashrrev_i32_e32 v45, 31, v44
	v_lshlrev_b64 v[44:45], s0, v[44:45]
	v_cvt_pk_bf16_f32 v39, v49, v51
	v_cvt_pk_bf16_f32 v40, v53, v55
	v_cvt_pk_bf16_f32 v41, v57, v59
	v_lshl_add_u64 v[42:43], v[44:45], 1, v[42:43]
	global_store_dwordx4 v[42:43], v[38:41], off nt
	s_waitcnt lgkmcnt(0)
	s_add_i32 s0, s45, s34
	s_cmpk_gt_i32 s0, 0x387f
	s_cbranch_scc1 .LBB0_1147
